# class barrier: the releasing workgroup no longer waits for its own release atomic to complete
# speedup vs baseline: 1.0096x; 1.0037x over previous
.Llb686_lead:
	global_atomic_add v197, v0, s[2:3] offset:2048
.Llb686_fin:
	s_branch .LBB0_686

.Llb790_lead:
	global_atomic_add v197, v0, s[2:3] offset:2048
.Llb790_fin:
	v_readfirstlane_b32 s1, v2
	v_readlane_b32 s0, v255, 31
	s_add_u32 s0, s0, 1
	s_lshl_b32 s0, s0, 8
	s_mov_b32 s9, 0

.Llb882_lead:
	global_atomic_add v197, v0, s[2:3] offset:2048
.Llb882_fin:
	s_branch .LBB0_882

.Llb962_lead:
	global_atomic_add v197, v0, s[2:3] offset:2048
.Llb962_fin:
	s_branch .LBB0_962
